# hand-off publishes: the first workgroup of each XCD to publish also starts an L2 write-back early (no wait); on top of the stacked version
# speedup vs baseline: 1.0021x; 1.0021x over previous
; #define HAND_PUBLISH(p) do { asm volatile("s_waitcnt vmcnt(0)" ::: "memory"); __syncthreads(); \
;                 if (otid() == 0) { __builtin_amdgcn_fence(__ATOMIC_RELEASE, "agent"); asm volatile("s_waitcnt vmcnt(0)" ::: "memory"); (void)xb_add((p), 1u); } } while (0)
; __global__ void __launch_bounds__(512, 2) mega(Params P) {
;     ...
;             run_gemm_sub(g_wave, lds, UP(U_MIX), WOl, MP, 1024, 1024, 0, G, bid, e);
;             HAND_PUBLISH(hand1);
.LBB0_1146:
	v_readlane_b32 s6, v254, 56
	s_lshl_b32 s10, s6, 6
	s_mov_b32 s1, s11
	v_readlane_b32 s7, v254, 57
	v_writelane_b32 v254, s0, 16
	s_lshl_b64 s[2:3], s[10:11], 2
	s_waitcnt vmcnt(0)
	s_waitcnt lgkmcnt(0)
	v_writelane_b32 v254, s1, 17
	s_add_u32 s0, s50, s2
	v_writelane_b32 v255, s2, 1
	s_addc_u32 s1, s51, s3
	s_add_u32 s10, s0, 0x39d0
	v_readlane_b32 s0, v253, 32
	s_barrier
	v_mbcnt_lo_u32_b32 v0, -1, 0
	v_mbcnt_hi_u32_b32 v0, -1, v0
	s_addc_u32 s11, s1, 0
	s_lshl_b32 s0, s0, 6
	v_sub_u32_e32 v0, 0, v0
	v_writelane_b32 v255, s3, 2
	v_cmp_eq_u32_e32 vcc, s0, v0
	s_and_saveexec_b64 s[0:1], vcc
	s_cbranch_execz .LBB0_1149
	s_getreg_b32 s12, hwreg(HW_REG_XCC_ID, 0, 4)
	s_and_b32 s12, s12, 15
	s_lshl_b32 s12, s12, 2
	v_mov_b32_e32 v72, 0x23fc8
	ds_read_b32 v73, v72
	v_mov_b32_e32 v74, s12
	v_mov_b32_e32 v75, 1
	global_atomic_add v76, v74, v75, s[10:11] offset:68 sc0
	s_waitcnt vmcnt(0) lgkmcnt(0)
	v_add_u32_e32 v76, 1, v76
	v_cmp_eq_u32_e32 vcc, 1, v76
	s_and_b64 vcc, exec, vcc
	s_cbranch_vccz .Lpub_h1_nofirst
	buffer_wbl2 sc1
.Lpub_h1_nofirst:
	v_cmp_eq_u32_e32 vcc, v76, v73
	s_and_b64 vcc, exec, vcc
	s_cbranch_vccz .Lpub_h1_skip
	buffer_wbl2 sc1
	s_waitcnt vmcnt(0)
	global_atomic_add v225, v73, s[10:11] offset:64

; #define otid() otid_w(g_wave)
; DI unsigned xb_add(unsigned* p, unsigned v) { return __hip_atomic_fetch_add(p, v, __ATOMIC_RELAXED, __HIP_MEMORY_SCOPE_AGENT); }
; __global__ void __launch_bounds__(512, 2) mega(Params P) {
;     ...
;             asm volatile("s_waitcnt vmcnt(0)" ::: "memory");
;             __syncthreads();
;             if (otid() == 0) { __builtin_amdgcn_fence(__ATOMIC_RELEASE, "agent"); asm volatile("s_waitcnt vmcnt(0)" ::: "memory"); (void)xb_add(WSP(unsigned, WS_CTL) + 3700 + 64 * l + 48, 1u); }
.LBB0_1660:
	s_mov_b32 s2, s21
	s_waitcnt vmcnt(0)
	s_waitcnt vmcnt(0) lgkmcnt(0)
	s_barrier
	v_mbcnt_lo_u32_b32 v0, -1, 0
	v_mbcnt_hi_u32_b32 v0, -1, v0
	s_lshl_b32 s2, s2, 6
	v_sub_u32_e32 v0, 0, v0
	v_cmp_eq_u32_e32 vcc, s2, v0
	s_and_saveexec_b64 s[2:3], vcc
	s_cbranch_execz .LBB0_1663
	v_readlane_b32 s6, v255, 1
	v_readlane_b32 s7, v255, 2
	s_add_u32 s6, s10, s6
	s_addc_u32 s7, s11, s7
	s_getreg_b32 s12, hwreg(HW_REG_XCC_ID, 0, 4)
	s_and_b32 s12, s12, 15
	s_lshl_b32 s12, s12, 2
	s_add_i32 s12, s12, 0x3000
	v_mov_b32_e32 v72, 0x23fc8
	ds_read_b32 v73, v72
	v_mov_b32_e32 v74, s12
	v_mov_b32_e32 v75, 1
	global_atomic_add v76, v74, v75, s[6:7] offset:2708 sc0
	s_waitcnt vmcnt(0) lgkmcnt(0)
	v_add_u32_e32 v76, 1, v76
	v_cmp_eq_u32_e32 vcc, 1, v76
	s_and_b64 vcc, exec, vcc
	s_cbranch_vccz .Lpub_hA_nofirst
	buffer_wbl2 sc1
.Lpub_hA_nofirst:
	v_cmp_eq_u32_e32 vcc, v76, v73
	s_and_b64 vcc, exec, vcc
	s_cbranch_vccz .Lpub_hA_skip
	buffer_wbl2 sc1
	s_waitcnt vmcnt(0)
	v_mov_b32_e32 v1, 0x3000
	global_atomic_add v1, v73, s[6:7] offset:2704
